# first K-iteration peeled with zero SrcC (no per-unit accumulator zeroing)
# speedup vs baseline: 1.0255x; 1.0042x over previous
; #define PG8_STAGE(bufoff, gbase, voff) do { _Pragma("unroll") for (int _i = 0; _i < 2; ++_i) \
;         __builtin_amdgcn_global_load_lds((const unsigned*)((const char*)(gbase) + (voff)[_i]), (PG8_LAS unsigned*)(lds + (bufoff) + ldsw + _i * 8192), 16, 0, 0); } while (0)
; #define PG8_LDA(dst, b, h) do { _Pragma("unroll") for (int m = 0; m < 4; ++m) _Pragma("unroll") for (int k = 0; k < 2; ++k) dst[m][k] = *(const PG8_LAS bf16x8*)(lds + PG8_SA(b, h) + aoff + m * 2048 + k * 1024); } while (0)
; #define PG8_LDB(dst, b, h) do { _Pragma("unroll") for (int n = 0; n < 2; ++n) _Pragma("unroll") for (int k = 0; k < 2; ++k) dst[n][k] = *(const PG8_LAS bf16x8*)(lds + PG8_SB(b, h) + boff + n * 2048 + k * 1024); } while (0)
; #define PG8_MMA(ai, bj, At, Bt) do { __builtin_amdgcn_s_setprio(1); _Pragma("unroll") for (int m = 0; m < 4; ++m) _Pragma("unroll") for (int n = 0; n < 2; ++n) _Pragma("unroll") for (int k = 0; k < 2; ++k) \
;         acc[ai][bj][m][n] = __builtin_amdgcn_mfma_f32_16x16x32_bf16(Bt[n][k], At[m][k], acc[ai][bj][m][n], 0, 0, 0); __builtin_amdgcn_s_setprio(0); } while (0)
; #define PG8_WAIT_V(n) asm volatile("s_waitcnt vmcnt(" #n ")" ::: "memory")
; #define PG8_WAIT_L(n) asm volatile("s_waitcnt lgkmcnt(" #n ")" ::: "memory")
; #define PG8_BAR __builtin_amdgcn_s_barrier()
; #define PG8_SCHED __builtin_amdgcn_sched_barrier(0)
; template <class Epi, class Sched, bool ALIGN_EPI = false, bool SP2 = false>
; __device__ __forceinline__ void gemm_phase(PG8_LAS unsigned char* lds, const Gemm g, const Sched& S, const Epi& E, const int tid_in) {
;     ...
;             if constexpr (SP2) {
;             PG8_LDB(B0, 0, 0); PG8_LDB(B1, 0, 1); PG8_SCHED; PG8_LDA(At, 0, 0); PG8_STAGE(PG8_SA(1, 1), a1 + hstepA, voffA);
;             PG8_WAIT_V(8); PG8_WAIT_L(0); PG8_BAR; PG8_MMA(0, 0, At, B0); PG8_MMA(0, 1, At, B1); PG8_BAR; PG8_SCHED;
;             PG8_LDA(At, 0, 1); PG8_STAGE(PG8_SB(0, 0), b2, voffB); PG8_STAGE(PG8_SB(0, 1), b2 + hstepB, voffB); PG8_STAGE(PG8_SA(0, 0), a2, voffA);
;             PG8_WAIT_V(8); PG8_WAIT_L(0); PG8_BAR; PG8_MMA(1, 0, At, B0); PG8_MMA(1, 1, At, B1); PG8_BAR; PG8_SCHED;
.LBB0_118:
	s_andn2_b64 vcc, exec, s[18:19]
	s_cbranch_vccnz .Lzero_acc_1
	s_add_u32 s26, s26, 0x4000
	s_addc_u32 s27, s27, 0
	s_add_u32 s6, s28, 0x8000
	s_addc_u32 s7, s29, 0
	s_mov_b32 s28, 0
	s_add_i32 s40, s28, 2
	s_add_u32 s4, s26, 0x4000
	s_addc_u32 s5, s27, 0
	s_cmp_eq_u32 s58, s28
	s_cselect_b32 s34, s22, s4
	s_cselect_b32 s35, s23, s5
	s_cselect_b32 s30, s24, s6
	s_cselect_b32 s31, s25, s7
	s_add_u32 s28, s34, 0x4000
	s_addc_u32 s29, s35, 0
	s_add_i32 s4, 0, 0x10000
	s_add_i32 s41, 0, 0x14000
	v_add_u32_e32 v152, s4, v138
	v_add_u32_e32 v168, s41, v138
	ds_read_b128 v[140:143], v152
	ds_read_b128 v[144:147], v152 offset:1024
	ds_read_b128 v[148:151], v152 offset:2048
	ds_read_b128 v[152:155], v152 offset:3072
	ds_read_b128 v[156:159], v168
	ds_read_b128 v[160:163], v168 offset:1024
	ds_read_b128 v[164:167], v168 offset:2048
	ds_read_b128 v[168:171], v168 offset:3072
	v_lshl_add_u64 v[206:207], s[26:27], 0, v[132:133]
	s_add_i32 m0, s11, 0xc000
	ds_read_b128 v[172:175], v139
	ds_read_b128 v[176:179], v139 offset:1024
	ds_read_b128 v[180:183], v139 offset:2048
	ds_read_b128 v[184:187], v139 offset:3072
	ds_read_b128 v[190:193], v139 offset:4096
	ds_read_b128 v[194:197], v139 offset:5120
	ds_read_b128 v[198:201], v139 offset:6144
	ds_read_b128 v[202:205], v139 offset:7168
	global_load_lds_dwordx4 v[206:207], off
	v_lshl_add_u64 v[206:207], s[26:27], 0, v[134:135]
	s_add_i32 m0, s11, 0xe000
	s_nop 0
	global_load_lds_dwordx4 v[206:207], off
	s_waitcnt vmcnt(8)
	s_waitcnt lgkmcnt(0)
	s_barrier
	s_setprio 1
	s_waitcnt lgkmcnt(0)
	v_mfma_f32_16x16x32_bf16 v[120:123], v[140:143], v[172:175], 0
	v_mfma_f32_16x16x32_bf16 v[124:127], v[148:151], v[172:175], 0
	v_mfma_f32_16x16x32_bf16 v[108:111], v[140:143], v[180:183], 0
	v_mfma_f32_16x16x32_bf16 v[104:107], v[148:151], v[180:183], 0
	v_mfma_f32_16x16x32_bf16 v[92:95], v[140:143], v[190:193], 0
	v_mfma_f32_16x16x32_bf16 v[88:91], v[148:151], v[190:193], 0
	v_mfma_f32_16x16x32_bf16 v[76:79], v[140:143], v[198:201], 0
	v_mfma_f32_16x16x32_bf16 v[72:75], v[148:151], v[198:201], 0
	v_mfma_f32_16x16x32_bf16 v[120:123], v[144:147], v[176:179], v[120:123]
	v_mfma_f32_16x16x32_bf16 v[124:127], v[152:155], v[176:179], v[124:127]
	v_mfma_f32_16x16x32_bf16 v[108:111], v[144:147], v[184:187], v[108:111]
	v_mfma_f32_16x16x32_bf16 v[104:107], v[152:155], v[184:187], v[104:107]
	v_mfma_f32_16x16x32_bf16 v[92:95], v[144:147], v[194:197], v[92:95]
	v_mfma_f32_16x16x32_bf16 v[88:91], v[152:155], v[194:197], v[88:91]
	v_mfma_f32_16x16x32_bf16 v[76:79], v[144:147], v[202:205], v[76:79]
	v_mfma_f32_16x16x32_bf16 v[72:75], v[152:155], v[202:205], v[72:75]
	s_setprio 0
	s_setprio 1
	v_mfma_f32_16x16x32_bf16 v[116:119], v[156:159], v[172:175], 0
	v_mfma_f32_16x16x32_bf16 v[112:115], v[164:167], v[172:175], 0
	v_mfma_f32_16x16x32_bf16 v[100:103], v[156:159], v[180:183], 0
	v_mfma_f32_16x16x32_bf16 v[96:99], v[164:167], v[180:183], 0
	v_mfma_f32_16x16x32_bf16 v[84:87], v[156:159], v[190:193], 0
	v_mfma_f32_16x16x32_bf16 v[80:83], v[164:167], v[190:193], 0
	v_mfma_f32_16x16x32_bf16 v[68:71], v[156:159], v[198:201], 0
	v_mfma_f32_16x16x32_bf16 v[64:67], v[164:167], v[198:201], 0
	v_mfma_f32_16x16x32_bf16 v[116:119], v[160:163], v[176:179], v[116:119]
	v_mfma_f32_16x16x32_bf16 v[112:115], v[168:171], v[176:179], v[112:115]
	v_mfma_f32_16x16x32_bf16 v[100:103], v[160:163], v[184:187], v[100:103]
	v_mfma_f32_16x16x32_bf16 v[96:99], v[168:171], v[184:187], v[96:99]
	v_mfma_f32_16x16x32_bf16 v[84:87], v[160:163], v[194:197], v[84:87]
	v_mfma_f32_16x16x32_bf16 v[80:83], v[168:171], v[194:197], v[80:83]
	v_mfma_f32_16x16x32_bf16 v[68:71], v[160:163], v[202:205], v[68:71]
	v_mfma_f32_16x16x32_bf16 v[64:67], v[168:171], v[202:205], v[64:67]
	s_setprio 0
	s_barrier
	s_add_i32 s4, s4, s0
	v_lshl_add_u64 v[206:207], s[30:31], 0, v[128:129]
	s_mov_b32 m0, s4
	ds_read_b128 v[172:175], v139 offset:16384
	ds_read_b128 v[176:179], v139 offset:17408
	ds_read_b128 v[180:183], v139 offset:18432
	ds_read_b128 v[184:187], v139 offset:19456
	ds_read_b128 v[190:193], v139 offset:20480
	ds_read_b128 v[194:197], v139 offset:21504
	ds_read_b128 v[198:201], v139 offset:22528
	ds_read_b128 v[202:205], v139 offset:23552
	global_load_lds_dwordx4 v[206:207], off
	s_add_i32 m0, s4, 0x2000
	s_add_u32 s4, s30, s12
	v_lshl_add_u64 v[206:207], s[30:31], 0, v[130:131]
	s_addc_u32 s5, s31, s13
	s_add_i32 s41, s41, s0
	global_load_lds_dwordx4 v[206:207], off
	v_lshl_add_u64 v[206:207], s[4:5], 0, v[128:129]
	s_mov_b32 m0, s41
	s_nop 0
	global_load_lds_dwordx4 v[206:207], off
	v_lshl_add_u64 v[206:207], s[4:5], 0, v[130:131]
	s_add_i32 m0, s41, 0x2000
	s_nop 0
	global_load_lds_dwordx4 v[206:207], off
	v_lshl_add_u64 v[206:207], s[34:35], 0, v[128:129]
	s_mov_b32 m0, s11
	s_nop 0
	global_load_lds_dwordx4 v[206:207], off
	v_lshl_add_u64 v[206:207], s[34:35], 0, v[130:131]
	s_mov_b32 m0, s48
	s_nop 0
	global_load_lds_dwordx4 v[206:207], off
	s_waitcnt vmcnt(8)
	s_waitcnt lgkmcnt(0)
	s_barrier
; #define PG8_STAGE(bufoff, gbase, voff) do { _Pragma("unroll") for (int _i = 0; _i < 2; ++_i) \
;         __builtin_amdgcn_global_load_lds((const unsigned*)((const char*)(gbase) + (voff)[_i]), (PG8_LAS unsigned*)(lds + (bufoff) + ldsw + _i * 8192), 16, 0, 0); } while (0)
; #define PG8_LDA(dst, b, h) do { _Pragma("unroll") for (int m = 0; m < 4; ++m) _Pragma("unroll") for (int k = 0; k < 2; ++k) dst[m][k] = *(const PG8_LAS bf16x8*)(lds + PG8_SA(b, h) + aoff + m * 2048 + k * 1024); } while (0)
; #define PG8_LDB(dst, b, h) do { _Pragma("unroll") for (int n = 0; n < 2; ++n) _Pragma("unroll") for (int k = 0; k < 2; ++k) dst[n][k] = *(const PG8_LAS bf16x8*)(lds + PG8_SB(b, h) + boff + n * 2048 + k * 1024); } while (0)
; #define PG8_MMA(ai, bj, At, Bt) do { __builtin_amdgcn_s_setprio(1); _Pragma("unroll") for (int m = 0; m < 4; ++m) _Pragma("unroll") for (int n = 0; n < 2; ++n) _Pragma("unroll") for (int k = 0; k < 2; ++k) \
;         acc[ai][bj][m][n] = __builtin_amdgcn_mfma_f32_16x16x32_bf16(Bt[n][k], At[m][k], acc[ai][bj][m][n], 0, 0, 0); __builtin_amdgcn_s_setprio(0); } while (0)
; #define PG8_WAIT_V(n) asm volatile("s_waitcnt vmcnt(" #n ")" ::: "memory")
; #define PG8_WAIT_L(n) asm volatile("s_waitcnt lgkmcnt(" #n ")" ::: "memory")
; #define PG8_BAR __builtin_amdgcn_s_barrier()
; #define PG8_SCHED __builtin_amdgcn_sched_barrier(0)
; template <class Epi, class Sched, bool ALIGN_EPI = false, bool SP2 = false>
; __device__ __forceinline__ void gemm_phase(PG8_LAS unsigned char* lds, const Gemm g, const Sched& S, const Epi& E, const int tid_in) {
;     ...
;             PG8_LDA(At, 0, 1); PG8_STAGE(PG8_SB(0, 0), b2, voffB); PG8_STAGE(PG8_SB(0, 1), b2 + hstepB, voffB); PG8_STAGE(PG8_SA(0, 0), a2, voffA);
;             PG8_WAIT_V(8); PG8_WAIT_L(0); PG8_BAR; PG8_MMA(1, 0, At, B0); PG8_MMA(1, 1, At, B1); PG8_BAR; PG8_SCHED;
;             PG8_LDB(B0, 1, 0); PG8_LDB(B1, 1, 1); PG8_SCHED; PG8_LDA(At, 1, 0); PG8_STAGE(PG8_SA(0, 1), a2 + hstepA, voffA);
;             PG8_WAIT_V(8); PG8_WAIT_L(0); PG8_BAR; PG8_MMA(0, 0, At, B0); PG8_MMA(0, 1, At, B1); PG8_BAR; PG8_SCHED;
	s_setprio 1
	s_waitcnt lgkmcnt(0)
	v_mfma_f32_16x16x32_bf16 v[60:63], v[140:143], v[172:175], 0
	v_mfma_f32_16x16x32_bf16 v[56:59], v[148:151], v[172:175], 0
	v_mfma_f32_16x16x32_bf16 v[44:47], v[140:143], v[180:183], 0
	v_mfma_f32_16x16x32_bf16 v[40:43], v[148:151], v[180:183], 0
	v_mfma_f32_16x16x32_bf16 v[28:31], v[140:143], v[190:193], 0
	v_mfma_f32_16x16x32_bf16 v[24:27], v[148:151], v[190:193], 0
	v_mfma_f32_16x16x32_bf16 v[12:15], v[140:143], v[198:201], 0
	v_mfma_f32_16x16x32_bf16 v[8:11], v[148:151], v[198:201], 0
	v_mfma_f32_16x16x32_bf16 v[60:63], v[144:147], v[176:179], v[60:63]
	v_mfma_f32_16x16x32_bf16 v[56:59], v[152:155], v[176:179], v[56:59]
	v_mfma_f32_16x16x32_bf16 v[44:47], v[144:147], v[184:187], v[44:47]
	v_mfma_f32_16x16x32_bf16 v[40:43], v[152:155], v[184:187], v[40:43]
	v_mfma_f32_16x16x32_bf16 v[28:31], v[144:147], v[194:197], v[28:31]
	v_mfma_f32_16x16x32_bf16 v[24:27], v[152:155], v[194:197], v[24:27]
	v_mfma_f32_16x16x32_bf16 v[12:15], v[144:147], v[202:205], v[12:15]
	v_mfma_f32_16x16x32_bf16 v[8:11], v[152:155], v[202:205], v[8:11]
	s_setprio 0
	s_setprio 1
	v_mfma_f32_16x16x32_bf16 v[52:55], v[156:159], v[172:175], 0
	v_mfma_f32_16x16x32_bf16 v[48:51], v[164:167], v[172:175], 0
	v_mfma_f32_16x16x32_bf16 v[36:39], v[156:159], v[180:183], 0
	v_mfma_f32_16x16x32_bf16 v[32:35], v[164:167], v[180:183], 0
	v_mfma_f32_16x16x32_bf16 v[20:23], v[156:159], v[190:193], 0
	v_mfma_f32_16x16x32_bf16 v[16:19], v[164:167], v[190:193], 0
	v_mfma_f32_16x16x32_bf16 v[4:7], v[156:159], v[198:201], 0
	v_mfma_f32_16x16x32_bf16 v[0:3], v[164:167], v[198:201], 0
	v_mfma_f32_16x16x32_bf16 v[52:55], v[160:163], v[176:179], v[52:55]
	v_mfma_f32_16x16x32_bf16 v[48:51], v[168:171], v[176:179], v[48:51]
	v_mfma_f32_16x16x32_bf16 v[36:39], v[160:163], v[184:187], v[36:39]
	v_mfma_f32_16x16x32_bf16 v[32:35], v[168:171], v[184:187], v[32:35]
	v_mfma_f32_16x16x32_bf16 v[20:23], v[160:163], v[194:197], v[20:23]
	v_mfma_f32_16x16x32_bf16 v[16:19], v[168:171], v[194:197], v[16:19]
	v_mfma_f32_16x16x32_bf16 v[4:7], v[160:163], v[202:205], v[4:7]
	v_mfma_f32_16x16x32_bf16 v[0:3], v[168:171], v[202:205], v[0:3]
	s_setprio 0
	s_barrier
	s_add_i32 s41, 0, 0x18000
	s_add_i32 s71, 0, 0x1c000
	v_add_u32_e32 v152, s41, v138
	v_add_u32_e32 v168, s71, v138
	ds_read_b128 v[140:143], v152
	ds_read_b128 v[144:147], v152 offset:1024
	ds_read_b128 v[148:151], v152 offset:2048
	ds_read_b128 v[152:155], v152 offset:3072
	ds_read_b128 v[156:159], v168
	ds_read_b128 v[160:163], v168 offset:1024
	ds_read_b128 v[164:167], v168 offset:2048
	ds_read_b128 v[168:171], v168 offset:3072
	s_add_u32 s4, s34, s12
	s_addc_u32 s5, s35, s13
	s_mov_b32 m0, s49
	v_lshl_add_u64 v[206:207], s[4:5], 0, v[128:129]
	ds_read_b128 v[172:175], v139 offset:32768
	ds_read_b128 v[176:179], v139 offset:33792
	ds_read_b128 v[180:183], v139 offset:34816
	ds_read_b128 v[184:187], v139 offset:35840
	ds_read_b128 v[190:193], v139 offset:36864
	ds_read_b128 v[194:197], v139 offset:37888
	ds_read_b128 v[198:201], v139 offset:38912
	ds_read_b128 v[202:205], v139 offset:39936
	global_load_lds_dwordx4 v[206:207], off
	v_lshl_add_u64 v[206:207], s[4:5], 0, v[130:131]
	s_mov_b32 m0, s50
	s_nop 0
	global_load_lds_dwordx4 v[206:207], off
	s_waitcnt vmcnt(8)
	s_waitcnt lgkmcnt(0)
	s_barrier
	s_setprio 1
	s_waitcnt lgkmcnt(0)
	v_mfma_f32_16x16x32_bf16 v[120:123], v[140:143], v[172:175], v[120:123]
	v_mfma_f32_16x16x32_bf16 v[124:127], v[148:151], v[172:175], v[124:127]
	v_mfma_f32_16x16x32_bf16 v[108:111], v[140:143], v[180:183], v[108:111]
	v_mfma_f32_16x16x32_bf16 v[104:107], v[148:151], v[180:183], v[104:107]
	v_mfma_f32_16x16x32_bf16 v[92:95], v[140:143], v[190:193], v[92:95]
	v_mfma_f32_16x16x32_bf16 v[88:91], v[148:151], v[190:193], v[88:91]
	v_mfma_f32_16x16x32_bf16 v[76:79], v[140:143], v[198:201], v[76:79]
	v_mfma_f32_16x16x32_bf16 v[72:75], v[148:151], v[198:201], v[72:75]
	v_mfma_f32_16x16x32_bf16 v[120:123], v[144:147], v[176:179], v[120:123]
	v_mfma_f32_16x16x32_bf16 v[124:127], v[152:155], v[176:179], v[124:127]
	v_mfma_f32_16x16x32_bf16 v[108:111], v[144:147], v[184:187], v[108:111]
	v_mfma_f32_16x16x32_bf16 v[104:107], v[152:155], v[184:187], v[104:107]
	v_mfma_f32_16x16x32_bf16 v[92:95], v[144:147], v[194:197], v[92:95]
	v_mfma_f32_16x16x32_bf16 v[88:91], v[152:155], v[194:197], v[88:91]
	v_mfma_f32_16x16x32_bf16 v[76:79], v[144:147], v[202:205], v[76:79]
	v_mfma_f32_16x16x32_bf16 v[72:75], v[152:155], v[202:205], v[72:75]
	s_setprio 0
	s_setprio 1
	v_mfma_f32_16x16x32_bf16 v[116:119], v[156:159], v[172:175], v[116:119]
	v_mfma_f32_16x16x32_bf16 v[112:115], v[164:167], v[172:175], v[112:115]
	v_mfma_f32_16x16x32_bf16 v[100:103], v[156:159], v[180:183], v[100:103]
	v_mfma_f32_16x16x32_bf16 v[96:99], v[164:167], v[180:183], v[96:99]
	v_mfma_f32_16x16x32_bf16 v[84:87], v[156:159], v[190:193], v[84:87]
	v_mfma_f32_16x16x32_bf16 v[80:83], v[164:167], v[190:193], v[80:83]
	v_mfma_f32_16x16x32_bf16 v[68:71], v[156:159], v[198:201], v[68:71]
	v_mfma_f32_16x16x32_bf16 v[64:67], v[164:167], v[198:201], v[64:67]
	v_mfma_f32_16x16x32_bf16 v[116:119], v[160:163], v[176:179], v[116:119]
	v_mfma_f32_16x16x32_bf16 v[112:115], v[168:171], v[176:179], v[112:115]
	v_mfma_f32_16x16x32_bf16 v[100:103], v[160:163], v[184:187], v[100:103]
	v_mfma_f32_16x16x32_bf16 v[96:99], v[168:171], v[184:187], v[96:99]
	v_mfma_f32_16x16x32_bf16 v[84:87], v[160:163], v[194:197], v[84:87]
	v_mfma_f32_16x16x32_bf16 v[80:83], v[168:171], v[194:197], v[80:83]
	v_mfma_f32_16x16x32_bf16 v[68:71], v[160:163], v[202:205], v[68:71]
	v_mfma_f32_16x16x32_bf16 v[64:67], v[168:171], v[202:205], v[64:67]
	s_setprio 0
	s_barrier
; #define PG8_STAGE(bufoff, gbase, voff) do { _Pragma("unroll") for (int _i = 0; _i < 2; ++_i) \
;         __builtin_amdgcn_global_load_lds((const unsigned*)((const char*)(gbase) + (voff)[_i]), (PG8_LAS unsigned*)(lds + (bufoff) + ldsw + _i * 8192), 16, 0, 0); } while (0)
; #define PG8_LDA(dst, b, h) do { _Pragma("unroll") for (int m = 0; m < 4; ++m) _Pragma("unroll") for (int k = 0; k < 2; ++k) dst[m][k] = *(const PG8_LAS bf16x8*)(lds + PG8_SA(b, h) + aoff + m * 2048 + k * 1024); } while (0)
; #define PG8_MMA(ai, bj, At, Bt) do { __builtin_amdgcn_s_setprio(1); _Pragma("unroll") for (int m = 0; m < 4; ++m) _Pragma("unroll") for (int n = 0; n < 2; ++n) _Pragma("unroll") for (int k = 0; k < 2; ++k) \
;         acc[ai][bj][m][n] = __builtin_amdgcn_mfma_f32_16x16x32_bf16(Bt[n][k], At[m][k], acc[ai][bj][m][n], 0, 0, 0); __builtin_amdgcn_s_setprio(0); } while (0)
; #define PG8_WAIT_V(n) asm volatile("s_waitcnt vmcnt(" #n ")" ::: "memory")
; #define PG8_WAIT_L(n) asm volatile("s_waitcnt lgkmcnt(" #n ")" ::: "memory")
; #define PG8_BAR __builtin_amdgcn_s_barrier()
; #define PG8_SCHED __builtin_amdgcn_sched_barrier(0)
; template <class Epi, class Sched, bool ALIGN_EPI = false, bool SP2 = false>
; __device__ __forceinline__ void gemm_phase(PG8_LAS unsigned char* lds, const Gemm g, const Sched& S, const Epi& E, const int tid_in) {
;     ...
;         for (int t = 0; t < nt; t += 2) {
;             const bool last = (t == nt - 2);
;             const char* a1 = cA + (size_t)(t + 1) * kstepA;
;             const char* a2 = last ? nA : cA + (size_t)(t + 2) * kstepA; const char* b2 = last ? nB : cB + (size_t)(t + 2) * kstepB;
;             const char* a3 = a2 + kstepA; const char* b3 = b2 + kstepB;
;     ...
;             PG8_WAIT_V(8); PG8_WAIT_L(0); PG8_BAR; PG8_MMA(0, 0, At, B0); PG8_MMA(0, 1, At, B1); PG8_BAR; PG8_SCHED;
;             PG8_LDA(At, 1, 1); PG8_STAGE(PG8_SB(1, 0), b3, voffB); PG8_STAGE(PG8_SB(1, 1), b3 + hstepB, voffB); PG8_STAGE(PG8_SA(1, 0), a3, voffA);
;             PG8_WAIT_V(8); PG8_WAIT_L(0); PG8_BAR; PG8_MMA(1, 0, At, B0); PG8_MMA(1, 1, At, B1); PG8_BAR; PG8_SCHED;
	s_add_u32 s4, s30, 0x4000
	s_addc_u32 s5, s31, 0
	s_add_i32 s30, s41, s0
	v_lshl_add_u64 v[206:207], s[4:5], 0, v[128:129]
	s_mov_b32 m0, s30
	ds_read_b128 v[172:175], v139 offset:49152
	ds_read_b128 v[176:179], v139 offset:50176
	ds_read_b128 v[180:183], v139 offset:51200
	ds_read_b128 v[184:187], v139 offset:52224
	ds_read_b128 v[190:193], v139 offset:53248
	ds_read_b128 v[194:197], v139 offset:54272
	ds_read_b128 v[198:201], v139 offset:55296
	ds_read_b128 v[202:205], v139 offset:56320
	global_load_lds_dwordx4 v[206:207], off
	s_add_i32 m0, s30, 0x2000
	v_lshl_add_u64 v[206:207], s[4:5], 0, v[130:131]
	s_add_u32 s4, s4, s12
	s_addc_u32 s5, s5, s13
	s_add_i32 s30, s71, s0
	global_load_lds_dwordx4 v[206:207], off
	v_lshl_add_u64 v[206:207], s[4:5], 0, v[128:129]
	s_mov_b32 m0, s30
	s_nop 0
	global_load_lds_dwordx4 v[206:207], off
	v_lshl_add_u64 v[206:207], s[4:5], 0, v[130:131]
	s_add_i32 m0, s30, 0x2000
	s_nop 0
	global_load_lds_dwordx4 v[206:207], off
	v_lshl_add_u64 v[206:207], s[28:29], 0, v[128:129]
	s_mov_b32 m0, s56
	s_nop 0
	global_load_lds_dwordx4 v[206:207], off
	v_lshl_add_u64 v[206:207], s[28:29], 0, v[130:131]
	s_mov_b32 m0, s57
	s_nop 0
	global_load_lds_dwordx4 v[206:207], off
	s_waitcnt vmcnt(8)
	s_waitcnt lgkmcnt(0)
	s_barrier
	s_setprio 1
	s_waitcnt lgkmcnt(0)
	v_mfma_f32_16x16x32_bf16 v[60:63], v[140:143], v[172:175], v[60:63]
	v_mfma_f32_16x16x32_bf16 v[56:59], v[148:151], v[172:175], v[56:59]
	v_mfma_f32_16x16x32_bf16 v[44:47], v[140:143], v[180:183], v[44:47]
	v_mfma_f32_16x16x32_bf16 v[40:43], v[148:151], v[180:183], v[40:43]
	v_mfma_f32_16x16x32_bf16 v[28:31], v[140:143], v[190:193], v[28:31]
	v_mfma_f32_16x16x32_bf16 v[24:27], v[148:151], v[190:193], v[24:27]
	v_mfma_f32_16x16x32_bf16 v[12:15], v[140:143], v[198:201], v[12:15]
	v_mfma_f32_16x16x32_bf16 v[8:11], v[148:151], v[198:201], v[8:11]
	v_mfma_f32_16x16x32_bf16 v[60:63], v[144:147], v[176:179], v[60:63]
	v_mfma_f32_16x16x32_bf16 v[56:59], v[152:155], v[176:179], v[56:59]
	v_mfma_f32_16x16x32_bf16 v[44:47], v[144:147], v[184:187], v[44:47]
	v_mfma_f32_16x16x32_bf16 v[40:43], v[152:155], v[184:187], v[40:43]
	v_mfma_f32_16x16x32_bf16 v[28:31], v[144:147], v[194:197], v[28:31]
	v_mfma_f32_16x16x32_bf16 v[24:27], v[152:155], v[194:197], v[24:27]
	v_mfma_f32_16x16x32_bf16 v[12:15], v[144:147], v[202:205], v[12:15]
	v_mfma_f32_16x16x32_bf16 v[8:11], v[152:155], v[202:205], v[8:11]
	s_setprio 0
	s_setprio 1
	v_mfma_f32_16x16x32_bf16 v[52:55], v[156:159], v[172:175], v[52:55]
	v_mfma_f32_16x16x32_bf16 v[48:51], v[164:167], v[172:175], v[48:51]
	v_mfma_f32_16x16x32_bf16 v[36:39], v[156:159], v[180:183], v[36:39]
	v_mfma_f32_16x16x32_bf16 v[32:35], v[164:167], v[180:183], v[32:35]
	v_mfma_f32_16x16x32_bf16 v[20:23], v[156:159], v[190:193], v[20:23]
	v_mfma_f32_16x16x32_bf16 v[16:19], v[164:167], v[190:193], v[16:19]
	v_mfma_f32_16x16x32_bf16 v[4:7], v[156:159], v[198:201], v[4:7]
	v_mfma_f32_16x16x32_bf16 v[0:3], v[164:167], v[198:201], v[0:3]
	v_mfma_f32_16x16x32_bf16 v[52:55], v[160:163], v[176:179], v[52:55]
	v_mfma_f32_16x16x32_bf16 v[48:51], v[168:171], v[176:179], v[48:51]
	v_mfma_f32_16x16x32_bf16 v[36:39], v[160:163], v[184:187], v[36:39]
	v_mfma_f32_16x16x32_bf16 v[32:35], v[168:171], v[184:187], v[32:35]
	v_mfma_f32_16x16x32_bf16 v[20:23], v[160:163], v[194:197], v[20:23]
	v_mfma_f32_16x16x32_bf16 v[16:19], v[168:171], v[194:197], v[16:19]
	v_mfma_f32_16x16x32_bf16 v[4:7], v[160:163], v[202:205], v[4:7]
	v_mfma_f32_16x16x32_bf16 v[0:3], v[168:171], v[202:205], v[0:3]
	s_setprio 0
	s_barrier
	s_add_u32 s26, s26, 0x8000
	s_addc_u32 s27, s27, 0
	s_add_u32 s6, s6, 0x8000
	s_addc_u32 s7, s7, 0
	s_cmp_ge_i32 s40, s10
	s_mov_b32 s28, s40
	s_cbranch_scc1 .LBB0_121

; #define PG8_STAGE(bufoff, gbase, voff) do { _Pragma("unroll") for (int _i = 0; _i < 2; ++_i) \
;         __builtin_amdgcn_global_load_lds((const unsigned*)((const char*)(gbase) + (voff)[_i]), (PG8_LAS unsigned*)(lds + (bufoff) + ldsw + _i * 8192), 16, 0, 0); } while (0)
; #define PG8_LDA(dst, b, h) do { _Pragma("unroll") for (int m = 0; m < 4; ++m) _Pragma("unroll") for (int k = 0; k < 2; ++k) dst[m][k] = *(const PG8_LAS bf16x8*)(lds + PG8_SA(b, h) + aoff + m * 2048 + k * 1024); } while (0)
; #define PG8_LDB(dst, b, h) do { _Pragma("unroll") for (int n = 0; n < 2; ++n) _Pragma("unroll") for (int k = 0; k < 2; ++k) dst[n][k] = *(const PG8_LAS bf16x8*)(lds + PG8_SB(b, h) + boff + n * 2048 + k * 1024); } while (0)
; #define PG8_MMA(ai, bj, At, Bt) do { __builtin_amdgcn_s_setprio(1); _Pragma("unroll") for (int m = 0; m < 4; ++m) _Pragma("unroll") for (int n = 0; n < 2; ++n) _Pragma("unroll") for (int k = 0; k < 2; ++k) \
;         acc[ai][bj][m][n] = __builtin_amdgcn_mfma_f32_16x16x32_bf16(Bt[n][k], At[m][k], acc[ai][bj][m][n], 0, 0, 0); __builtin_amdgcn_s_setprio(0); } while (0)
; #define PG8_WAIT_V(n) asm volatile("s_waitcnt vmcnt(" #n ")" ::: "memory")
; #define PG8_WAIT_L(n) asm volatile("s_waitcnt lgkmcnt(" #n ")" ::: "memory")
; #define PG8_BAR __builtin_amdgcn_s_barrier()
; #define PG8_SCHED __builtin_amdgcn_sched_barrier(0)
; template <class Epi, class Sched, bool ALIGN_EPI = false, bool SP2 = false>
; __device__ __forceinline__ void gemm_phase(PG8_LAS unsigned char* lds, const Gemm g, const Sched& S, const Epi& E, const int tid_in) {
;     ...
;             if constexpr (SP2) {
;             PG8_LDB(B0, 0, 0); PG8_LDB(B1, 0, 1); PG8_SCHED; PG8_LDA(At, 0, 0); PG8_STAGE(PG8_SA(1, 1), a1 + hstepA, voffA);
;             PG8_WAIT_V(8); PG8_WAIT_L(0); PG8_BAR; PG8_MMA(0, 0, At, B0); PG8_MMA(0, 1, At, B1); PG8_BAR; PG8_SCHED;
;             PG8_LDA(At, 0, 1); PG8_STAGE(PG8_SB(0, 0), b2, voffB); PG8_STAGE(PG8_SB(0, 1), b2 + hstepB, voffB); PG8_STAGE(PG8_SA(0, 0), a2, voffA);
;             PG8_WAIT_V(8); PG8_WAIT_L(0); PG8_BAR; PG8_MMA(1, 0, At, B0); PG8_MMA(1, 1, At, B1); PG8_BAR; PG8_SCHED;
.LBB0_143:
	s_andn2_b64 vcc, exec, s[18:19]
	s_cbranch_vccnz .Lzero_acc_2
	s_add_u32 s26, s26, 0x4000
	s_addc_u32 s27, s27, 0
	s_add_u32 s6, s28, 0x8000
	s_addc_u32 s7, s29, 0
	s_mov_b32 s28, 0
	s_add_i32 s40, s28, 2
	s_add_u32 s4, s26, 0x4000
	s_addc_u32 s5, s27, 0
	s_cmp_eq_u32 s43, s28
	s_cselect_b32 s34, s22, s4
	s_cselect_b32 s35, s23, s5
	s_cselect_b32 s30, s24, s6
	s_cselect_b32 s31, s25, s7
	s_add_u32 s28, s34, 0x4000
	s_addc_u32 s29, s35, 0
	s_add_i32 s4, 0, 0x10000
	s_add_i32 s41, 0, 0x14000
	v_add_u32_e32 v140, s4, v190
	v_add_u32_e32 v166, s41, v190
	ds_read_b128 v[128:131], v140
	ds_read_b128 v[132:135], v140 offset:1024
	ds_read_b128 v[136:139], v140 offset:2048
	ds_read_b128 v[140:143], v140 offset:3072
	ds_read_b128 v[144:147], v166
	ds_read_b128 v[148:151], v166 offset:1024
	ds_read_b128 v[152:155], v166 offset:2048
	ds_read_b128 v[166:169], v166 offset:3072
	v_lshl_add_u64 v[186:187], s[26:27], 0, v[162:163]
	s_add_i32 m0, s1, 0xc000
	ds_read_b128 v[170:173], v194
	ds_read_b128 v[174:177], v194 offset:1024
	ds_read_b128 v[178:181], v194 offset:2048
	ds_read_b128 v[182:185], v194 offset:3072
	ds_read_b128 v[196:199], v194 offset:4096
	ds_read_b128 v[200:203], v194 offset:5120
	ds_read_b128 v[204:207], v194 offset:6144
	ds_read_b128 v[210:213], v194 offset:7168
	global_load_lds_dwordx4 v[186:187], off
	v_lshl_add_u64 v[186:187], s[26:27], 0, v[164:165]
	s_add_i32 m0, s1, 0xe000
	s_nop 0
	global_load_lds_dwordx4 v[186:187], off
	s_waitcnt vmcnt(8)
	s_waitcnt lgkmcnt(0)
	s_barrier
	s_setprio 1
	s_waitcnt lgkmcnt(0)
	v_mfma_f32_16x16x32_bf16 v[124:127], v[128:131], v[170:173], 0
	v_mfma_f32_16x16x32_bf16 v[120:123], v[136:139], v[170:173], 0
	v_mfma_f32_16x16x32_bf16 v[108:111], v[128:131], v[178:181], 0
	v_mfma_f32_16x16x32_bf16 v[104:107], v[136:139], v[178:181], 0
	v_mfma_f32_16x16x32_bf16 v[92:95], v[128:131], v[196:199], 0
	v_mfma_f32_16x16x32_bf16 v[88:91], v[136:139], v[196:199], 0
	v_mfma_f32_16x16x32_bf16 v[76:79], v[128:131], v[204:207], 0
	v_mfma_f32_16x16x32_bf16 v[72:75], v[136:139], v[204:207], 0
	v_mfma_f32_16x16x32_bf16 v[124:127], v[132:135], v[174:177], v[124:127]
	v_mfma_f32_16x16x32_bf16 v[120:123], v[140:143], v[174:177], v[120:123]
	v_mfma_f32_16x16x32_bf16 v[108:111], v[132:135], v[182:185], v[108:111]
	v_mfma_f32_16x16x32_bf16 v[104:107], v[140:143], v[182:185], v[104:107]
	v_mfma_f32_16x16x32_bf16 v[92:95], v[132:135], v[200:203], v[92:95]
	v_mfma_f32_16x16x32_bf16 v[88:91], v[140:143], v[200:203], v[88:91]
	v_mfma_f32_16x16x32_bf16 v[76:79], v[132:135], v[210:213], v[76:79]
	v_mfma_f32_16x16x32_bf16 v[72:75], v[140:143], v[210:213], v[72:75]
	s_setprio 0
	s_setprio 1
	v_mfma_f32_16x16x32_bf16 v[116:119], v[144:147], v[170:173], 0
	v_mfma_f32_16x16x32_bf16 v[112:115], v[152:155], v[170:173], 0
	v_mfma_f32_16x16x32_bf16 v[100:103], v[144:147], v[178:181], 0
	v_mfma_f32_16x16x32_bf16 v[96:99], v[152:155], v[178:181], 0
	v_mfma_f32_16x16x32_bf16 v[84:87], v[144:147], v[196:199], 0
	v_mfma_f32_16x16x32_bf16 v[80:83], v[152:155], v[196:199], 0
	v_mfma_f32_16x16x32_bf16 v[68:71], v[144:147], v[204:207], 0
	v_mfma_f32_16x16x32_bf16 v[64:67], v[152:155], v[204:207], 0
	v_mfma_f32_16x16x32_bf16 v[116:119], v[148:151], v[174:177], v[116:119]
	v_mfma_f32_16x16x32_bf16 v[112:115], v[166:169], v[174:177], v[112:115]
	v_mfma_f32_16x16x32_bf16 v[100:103], v[148:151], v[182:185], v[100:103]
	v_mfma_f32_16x16x32_bf16 v[96:99], v[166:169], v[182:185], v[96:99]
	v_mfma_f32_16x16x32_bf16 v[84:87], v[148:151], v[200:203], v[84:87]
	v_mfma_f32_16x16x32_bf16 v[80:83], v[166:169], v[200:203], v[80:83]
	v_mfma_f32_16x16x32_bf16 v[68:71], v[148:151], v[210:213], v[68:71]
	v_mfma_f32_16x16x32_bf16 v[64:67], v[166:169], v[210:213], v[64:67]
	s_setprio 0
	s_barrier
	s_add_i32 s4, s4, s0
	v_lshl_add_u64 v[186:187], s[30:31], 0, v[156:157]
	s_mov_b32 m0, s4
	ds_read_b128 v[170:173], v194 offset:16384
	ds_read_b128 v[174:177], v194 offset:17408
	ds_read_b128 v[178:181], v194 offset:18432
	ds_read_b128 v[182:185], v194 offset:19456
	ds_read_b128 v[196:199], v194 offset:20480
	ds_read_b128 v[200:203], v194 offset:21504
	ds_read_b128 v[204:207], v194 offset:22528
	ds_read_b128 v[210:213], v194 offset:23552
	global_load_lds_dwordx4 v[186:187], off
	s_add_i32 m0, s4, 0x2000
	s_add_u32 s4, s30, s12
	v_lshl_add_u64 v[186:187], s[30:31], 0, v[158:159]
	s_addc_u32 s5, s31, s13
	s_add_i32 s41, s41, s0
	global_load_lds_dwordx4 v[186:187], off
	v_lshl_add_u64 v[186:187], s[4:5], 0, v[156:157]
	s_mov_b32 m0, s41
	s_nop 0
	global_load_lds_dwordx4 v[186:187], off
	v_lshl_add_u64 v[186:187], s[4:5], 0, v[158:159]
	s_add_i32 m0, s41, 0x2000
	s_nop 0
	global_load_lds_dwordx4 v[186:187], off
	v_lshl_add_u64 v[186:187], s[34:35], 0, v[156:157]
	s_mov_b32 m0, s1
	s_nop 0
	global_load_lds_dwordx4 v[186:187], off
	v_lshl_add_u64 v[186:187], s[34:35], 0, v[158:159]
	s_mov_b32 m0, s3
	s_nop 0
	global_load_lds_dwordx4 v[186:187], off
	s_waitcnt vmcnt(8)
	s_waitcnt lgkmcnt(0)
	s_barrier
; #define PG8_STAGE(bufoff, gbase, voff) do { _Pragma("unroll") for (int _i = 0; _i < 2; ++_i) \
;         __builtin_amdgcn_global_load_lds((const unsigned*)((const char*)(gbase) + (voff)[_i]), (PG8_LAS unsigned*)(lds + (bufoff) + ldsw + _i * 8192), 16, 0, 0); } while (0)
; #define PG8_LDA(dst, b, h) do { _Pragma("unroll") for (int m = 0; m < 4; ++m) _Pragma("unroll") for (int k = 0; k < 2; ++k) dst[m][k] = *(const PG8_LAS bf16x8*)(lds + PG8_SA(b, h) + aoff + m * 2048 + k * 1024); } while (0)
; #define PG8_LDB(dst, b, h) do { _Pragma("unroll") for (int n = 0; n < 2; ++n) _Pragma("unroll") for (int k = 0; k < 2; ++k) dst[n][k] = *(const PG8_LAS bf16x8*)(lds + PG8_SB(b, h) + boff + n * 2048 + k * 1024); } while (0)
; #define PG8_MMA(ai, bj, At, Bt) do { __builtin_amdgcn_s_setprio(1); _Pragma("unroll") for (int m = 0; m < 4; ++m) _Pragma("unroll") for (int n = 0; n < 2; ++n) _Pragma("unroll") for (int k = 0; k < 2; ++k) \
;         acc[ai][bj][m][n] = __builtin_amdgcn_mfma_f32_16x16x32_bf16(Bt[n][k], At[m][k], acc[ai][bj][m][n], 0, 0, 0); __builtin_amdgcn_s_setprio(0); } while (0)
; #define PG8_WAIT_V(n) asm volatile("s_waitcnt vmcnt(" #n ")" ::: "memory")
; #define PG8_WAIT_L(n) asm volatile("s_waitcnt lgkmcnt(" #n ")" ::: "memory")
; #define PG8_BAR __builtin_amdgcn_s_barrier()
; #define PG8_SCHED __builtin_amdgcn_sched_barrier(0)
; template <class Epi, class Sched, bool ALIGN_EPI = false, bool SP2 = false>
; __device__ __forceinline__ void gemm_phase(PG8_LAS unsigned char* lds, const Gemm g, const Sched& S, const Epi& E, const int tid_in) {
;     ...
;             PG8_LDA(At, 0, 1); PG8_STAGE(PG8_SB(0, 0), b2, voffB); PG8_STAGE(PG8_SB(0, 1), b2 + hstepB, voffB); PG8_STAGE(PG8_SA(0, 0), a2, voffA);
;             PG8_WAIT_V(8); PG8_WAIT_L(0); PG8_BAR; PG8_MMA(1, 0, At, B0); PG8_MMA(1, 1, At, B1); PG8_BAR; PG8_SCHED;
;             PG8_LDB(B0, 1, 0); PG8_LDB(B1, 1, 1); PG8_SCHED; PG8_LDA(At, 1, 0); PG8_STAGE(PG8_SA(0, 1), a2 + hstepA, voffA);
;             PG8_WAIT_V(8); PG8_WAIT_L(0); PG8_BAR; PG8_MMA(0, 0, At, B0); PG8_MMA(0, 1, At, B1); PG8_BAR; PG8_SCHED;
	s_setprio 1
	s_waitcnt lgkmcnt(0)
	v_mfma_f32_16x16x32_bf16 v[60:63], v[128:131], v[170:173], 0
	v_mfma_f32_16x16x32_bf16 v[56:59], v[136:139], v[170:173], 0
	v_mfma_f32_16x16x32_bf16 v[44:47], v[128:131], v[178:181], 0
	v_mfma_f32_16x16x32_bf16 v[40:43], v[136:139], v[178:181], 0
	v_mfma_f32_16x16x32_bf16 v[28:31], v[128:131], v[196:199], 0
	v_mfma_f32_16x16x32_bf16 v[24:27], v[136:139], v[196:199], 0
	v_mfma_f32_16x16x32_bf16 v[12:15], v[128:131], v[204:207], 0
	v_mfma_f32_16x16x32_bf16 v[8:11], v[136:139], v[204:207], 0
	v_mfma_f32_16x16x32_bf16 v[60:63], v[132:135], v[174:177], v[60:63]
	v_mfma_f32_16x16x32_bf16 v[56:59], v[140:143], v[174:177], v[56:59]
	v_mfma_f32_16x16x32_bf16 v[44:47], v[132:135], v[182:185], v[44:47]
	v_mfma_f32_16x16x32_bf16 v[40:43], v[140:143], v[182:185], v[40:43]
	v_mfma_f32_16x16x32_bf16 v[28:31], v[132:135], v[200:203], v[28:31]
	v_mfma_f32_16x16x32_bf16 v[24:27], v[140:143], v[200:203], v[24:27]
	v_mfma_f32_16x16x32_bf16 v[12:15], v[132:135], v[210:213], v[12:15]
	v_mfma_f32_16x16x32_bf16 v[8:11], v[140:143], v[210:213], v[8:11]
	s_setprio 0
	s_setprio 1
	v_mfma_f32_16x16x32_bf16 v[52:55], v[144:147], v[170:173], 0
	v_mfma_f32_16x16x32_bf16 v[48:51], v[152:155], v[170:173], 0
	v_mfma_f32_16x16x32_bf16 v[36:39], v[144:147], v[178:181], 0
	v_mfma_f32_16x16x32_bf16 v[32:35], v[152:155], v[178:181], 0
	v_mfma_f32_16x16x32_bf16 v[20:23], v[144:147], v[196:199], 0
	v_mfma_f32_16x16x32_bf16 v[16:19], v[152:155], v[196:199], 0
	v_mfma_f32_16x16x32_bf16 v[4:7], v[144:147], v[204:207], 0
	v_mfma_f32_16x16x32_bf16 v[0:3], v[152:155], v[204:207], 0
	v_mfma_f32_16x16x32_bf16 v[52:55], v[148:151], v[174:177], v[52:55]
	v_mfma_f32_16x16x32_bf16 v[48:51], v[166:169], v[174:177], v[48:51]
	v_mfma_f32_16x16x32_bf16 v[36:39], v[148:151], v[182:185], v[36:39]
	v_mfma_f32_16x16x32_bf16 v[32:35], v[166:169], v[182:185], v[32:35]
	v_mfma_f32_16x16x32_bf16 v[20:23], v[148:151], v[200:203], v[20:23]
	v_mfma_f32_16x16x32_bf16 v[16:19], v[166:169], v[200:203], v[16:19]
	v_mfma_f32_16x16x32_bf16 v[4:7], v[148:151], v[210:213], v[4:7]
	v_mfma_f32_16x16x32_bf16 v[0:3], v[166:169], v[210:213], v[0:3]
	s_setprio 0
	s_barrier
	s_add_i32 s41, 0, 0x18000
	s_add_i32 s64, 0, 0x1c000
	v_add_u32_e32 v140, s41, v190
	v_add_u32_e32 v166, s64, v190
	ds_read_b128 v[128:131], v140
	ds_read_b128 v[132:135], v140 offset:1024
	ds_read_b128 v[136:139], v140 offset:2048
	ds_read_b128 v[140:143], v140 offset:3072
	ds_read_b128 v[144:147], v166
	ds_read_b128 v[148:151], v166 offset:1024
	ds_read_b128 v[152:155], v166 offset:2048
	ds_read_b128 v[166:169], v166 offset:3072
	s_add_u32 s4, s34, s12
	s_addc_u32 s5, s35, s13
	s_mov_b32 m0, s11
	v_lshl_add_u64 v[186:187], s[4:5], 0, v[156:157]
	ds_read_b128 v[170:173], v194 offset:32768
	ds_read_b128 v[174:177], v194 offset:33792
	ds_read_b128 v[178:181], v194 offset:34816
	ds_read_b128 v[182:185], v194 offset:35840
	ds_read_b128 v[196:199], v194 offset:36864
	ds_read_b128 v[200:203], v194 offset:37888
	ds_read_b128 v[204:207], v194 offset:38912
	ds_read_b128 v[210:213], v194 offset:39936
	global_load_lds_dwordx4 v[186:187], off
	v_lshl_add_u64 v[186:187], s[4:5], 0, v[158:159]
	s_mov_b32 m0, s33
	s_nop 0
	global_load_lds_dwordx4 v[186:187], off
	s_waitcnt vmcnt(8)
	s_waitcnt lgkmcnt(0)
	s_barrier
	s_setprio 1
	s_waitcnt lgkmcnt(0)
	v_mfma_f32_16x16x32_bf16 v[124:127], v[128:131], v[170:173], v[124:127]
	v_mfma_f32_16x16x32_bf16 v[120:123], v[136:139], v[170:173], v[120:123]
	v_mfma_f32_16x16x32_bf16 v[108:111], v[128:131], v[178:181], v[108:111]
	v_mfma_f32_16x16x32_bf16 v[104:107], v[136:139], v[178:181], v[104:107]
	v_mfma_f32_16x16x32_bf16 v[92:95], v[128:131], v[196:199], v[92:95]
	v_mfma_f32_16x16x32_bf16 v[88:91], v[136:139], v[196:199], v[88:91]
	v_mfma_f32_16x16x32_bf16 v[76:79], v[128:131], v[204:207], v[76:79]
	v_mfma_f32_16x16x32_bf16 v[72:75], v[136:139], v[204:207], v[72:75]
	v_mfma_f32_16x16x32_bf16 v[124:127], v[132:135], v[174:177], v[124:127]
	v_mfma_f32_16x16x32_bf16 v[120:123], v[140:143], v[174:177], v[120:123]
	v_mfma_f32_16x16x32_bf16 v[108:111], v[132:135], v[182:185], v[108:111]
	v_mfma_f32_16x16x32_bf16 v[104:107], v[140:143], v[182:185], v[104:107]
	v_mfma_f32_16x16x32_bf16 v[92:95], v[132:135], v[200:203], v[92:95]
	v_mfma_f32_16x16x32_bf16 v[88:91], v[140:143], v[200:203], v[88:91]
	v_mfma_f32_16x16x32_bf16 v[76:79], v[132:135], v[210:213], v[76:79]
	v_mfma_f32_16x16x32_bf16 v[72:75], v[140:143], v[210:213], v[72:75]
	s_setprio 0
	s_setprio 1
	v_mfma_f32_16x16x32_bf16 v[116:119], v[144:147], v[170:173], v[116:119]
	v_mfma_f32_16x16x32_bf16 v[112:115], v[152:155], v[170:173], v[112:115]
	v_mfma_f32_16x16x32_bf16 v[100:103], v[144:147], v[178:181], v[100:103]
	v_mfma_f32_16x16x32_bf16 v[96:99], v[152:155], v[178:181], v[96:99]
	v_mfma_f32_16x16x32_bf16 v[84:87], v[144:147], v[196:199], v[84:87]
	v_mfma_f32_16x16x32_bf16 v[80:83], v[152:155], v[196:199], v[80:83]
	v_mfma_f32_16x16x32_bf16 v[68:71], v[144:147], v[204:207], v[68:71]
	v_mfma_f32_16x16x32_bf16 v[64:67], v[152:155], v[204:207], v[64:67]
	v_mfma_f32_16x16x32_bf16 v[116:119], v[148:151], v[174:177], v[116:119]
	v_mfma_f32_16x16x32_bf16 v[112:115], v[166:169], v[174:177], v[112:115]
	v_mfma_f32_16x16x32_bf16 v[100:103], v[148:151], v[182:185], v[100:103]
	v_mfma_f32_16x16x32_bf16 v[96:99], v[166:169], v[182:185], v[96:99]
	v_mfma_f32_16x16x32_bf16 v[84:87], v[148:151], v[200:203], v[84:87]
	v_mfma_f32_16x16x32_bf16 v[80:83], v[166:169], v[200:203], v[80:83]
	v_mfma_f32_16x16x32_bf16 v[68:71], v[148:151], v[210:213], v[68:71]
	v_mfma_f32_16x16x32_bf16 v[64:67], v[166:169], v[210:213], v[64:67]
	s_setprio 0
	s_barrier
; #define PG8_STAGE(bufoff, gbase, voff) do { _Pragma("unroll") for (int _i = 0; _i < 2; ++_i) \
;         __builtin_amdgcn_global_load_lds((const unsigned*)((const char*)(gbase) + (voff)[_i]), (PG8_LAS unsigned*)(lds + (bufoff) + ldsw + _i * 8192), 16, 0, 0); } while (0)
; #define PG8_LDA(dst, b, h) do { _Pragma("unroll") for (int m = 0; m < 4; ++m) _Pragma("unroll") for (int k = 0; k < 2; ++k) dst[m][k] = *(const PG8_LAS bf16x8*)(lds + PG8_SA(b, h) + aoff + m * 2048 + k * 1024); } while (0)
; #define PG8_MMA(ai, bj, At, Bt) do { __builtin_amdgcn_s_setprio(1); _Pragma("unroll") for (int m = 0; m < 4; ++m) _Pragma("unroll") for (int n = 0; n < 2; ++n) _Pragma("unroll") for (int k = 0; k < 2; ++k) \
;         acc[ai][bj][m][n] = __builtin_amdgcn_mfma_f32_16x16x32_bf16(Bt[n][k], At[m][k], acc[ai][bj][m][n], 0, 0, 0); __builtin_amdgcn_s_setprio(0); } while (0)
; #define PG8_WAIT_V(n) asm volatile("s_waitcnt vmcnt(" #n ")" ::: "memory")
; #define PG8_WAIT_L(n) asm volatile("s_waitcnt lgkmcnt(" #n ")" ::: "memory")
; #define PG8_BAR __builtin_amdgcn_s_barrier()
; #define PG8_SCHED __builtin_amdgcn_sched_barrier(0)
; template <class Epi, class Sched, bool ALIGN_EPI = false, bool SP2 = false>
; __device__ __forceinline__ void gemm_phase(PG8_LAS unsigned char* lds, const Gemm g, const Sched& S, const Epi& E, const int tid_in) {
;     ...
;         for (int t = 0; t < nt; t += 2) {
;             const bool last = (t == nt - 2);
;             const char* a1 = cA + (size_t)(t + 1) * kstepA;
;             const char* a2 = last ? nA : cA + (size_t)(t + 2) * kstepA; const char* b2 = last ? nB : cB + (size_t)(t + 2) * kstepB;
;             const char* a3 = a2 + kstepA; const char* b3 = b2 + kstepB;
;     ...
;             PG8_LDA(At, 1, 1); PG8_STAGE(PG8_SB(1, 0), b3, voffB); PG8_STAGE(PG8_SB(1, 1), b3 + hstepB, voffB); PG8_STAGE(PG8_SA(1, 0), a3, voffA);
;             PG8_WAIT_V(8); PG8_WAIT_L(0); PG8_BAR; PG8_MMA(1, 0, At, B0); PG8_MMA(1, 1, At, B1); PG8_BAR; PG8_SCHED;
	s_add_u32 s4, s30, 0x4000
	s_addc_u32 s5, s31, 0
	s_add_i32 s30, s41, s0
	v_lshl_add_u64 v[186:187], s[4:5], 0, v[156:157]
	s_mov_b32 m0, s30
	ds_read_b128 v[170:173], v194 offset:49152
	ds_read_b128 v[174:177], v194 offset:50176
	ds_read_b128 v[178:181], v194 offset:51200
	ds_read_b128 v[182:185], v194 offset:52224
	ds_read_b128 v[196:199], v194 offset:53248
	ds_read_b128 v[200:203], v194 offset:54272
	ds_read_b128 v[204:207], v194 offset:55296
	ds_read_b128 v[210:213], v194 offset:56320
	global_load_lds_dwordx4 v[186:187], off
	s_add_i32 m0, s30, 0x2000
	v_lshl_add_u64 v[186:187], s[4:5], 0, v[158:159]
	s_add_u32 s4, s4, s12
	s_addc_u32 s5, s5, s13
	s_add_i32 s30, s64, s0
	global_load_lds_dwordx4 v[186:187], off
	v_lshl_add_u64 v[186:187], s[4:5], 0, v[156:157]
	s_mov_b32 m0, s30
	s_nop 0
	global_load_lds_dwordx4 v[186:187], off
	v_lshl_add_u64 v[186:187], s[4:5], 0, v[158:159]
	s_add_i32 m0, s30, 0x2000
	s_nop 0
	global_load_lds_dwordx4 v[186:187], off
	v_lshl_add_u64 v[186:187], s[28:29], 0, v[156:157]
	s_mov_b32 m0, s37
	s_nop 0
	global_load_lds_dwordx4 v[186:187], off
	v_lshl_add_u64 v[186:187], s[28:29], 0, v[158:159]
	s_mov_b32 m0, s42
	s_nop 0
	global_load_lds_dwordx4 v[186:187], off
	s_waitcnt vmcnt(8)
	s_waitcnt lgkmcnt(0)
	s_barrier
	s_setprio 1
	s_waitcnt lgkmcnt(0)
	v_mfma_f32_16x16x32_bf16 v[60:63], v[128:131], v[170:173], v[60:63]
	v_mfma_f32_16x16x32_bf16 v[56:59], v[136:139], v[170:173], v[56:59]
	v_mfma_f32_16x16x32_bf16 v[44:47], v[128:131], v[178:181], v[44:47]
	v_mfma_f32_16x16x32_bf16 v[40:43], v[136:139], v[178:181], v[40:43]
	v_mfma_f32_16x16x32_bf16 v[28:31], v[128:131], v[196:199], v[28:31]
	v_mfma_f32_16x16x32_bf16 v[24:27], v[136:139], v[196:199], v[24:27]
	v_mfma_f32_16x16x32_bf16 v[12:15], v[128:131], v[204:207], v[12:15]
	v_mfma_f32_16x16x32_bf16 v[8:11], v[136:139], v[204:207], v[8:11]
	v_mfma_f32_16x16x32_bf16 v[60:63], v[132:135], v[174:177], v[60:63]
	v_mfma_f32_16x16x32_bf16 v[56:59], v[140:143], v[174:177], v[56:59]
	v_mfma_f32_16x16x32_bf16 v[44:47], v[132:135], v[182:185], v[44:47]
	v_mfma_f32_16x16x32_bf16 v[40:43], v[140:143], v[182:185], v[40:43]
	v_mfma_f32_16x16x32_bf16 v[28:31], v[132:135], v[200:203], v[28:31]
	v_mfma_f32_16x16x32_bf16 v[24:27], v[140:143], v[200:203], v[24:27]
	v_mfma_f32_16x16x32_bf16 v[12:15], v[132:135], v[210:213], v[12:15]
	v_mfma_f32_16x16x32_bf16 v[8:11], v[140:143], v[210:213], v[8:11]
	s_setprio 0
	s_setprio 1
	v_mfma_f32_16x16x32_bf16 v[52:55], v[144:147], v[170:173], v[52:55]
	v_mfma_f32_16x16x32_bf16 v[48:51], v[152:155], v[170:173], v[48:51]
	v_mfma_f32_16x16x32_bf16 v[36:39], v[144:147], v[178:181], v[36:39]
	v_mfma_f32_16x16x32_bf16 v[32:35], v[152:155], v[178:181], v[32:35]
	v_mfma_f32_16x16x32_bf16 v[20:23], v[144:147], v[196:199], v[20:23]
	v_mfma_f32_16x16x32_bf16 v[16:19], v[152:155], v[196:199], v[16:19]
	v_mfma_f32_16x16x32_bf16 v[4:7], v[144:147], v[204:207], v[4:7]
	v_mfma_f32_16x16x32_bf16 v[0:3], v[152:155], v[204:207], v[0:3]
	v_mfma_f32_16x16x32_bf16 v[52:55], v[148:151], v[174:177], v[52:55]
	v_mfma_f32_16x16x32_bf16 v[48:51], v[166:169], v[174:177], v[48:51]
	v_mfma_f32_16x16x32_bf16 v[36:39], v[148:151], v[182:185], v[36:39]
	v_mfma_f32_16x16x32_bf16 v[32:35], v[166:169], v[182:185], v[32:35]
	v_mfma_f32_16x16x32_bf16 v[20:23], v[148:151], v[200:203], v[20:23]
	v_mfma_f32_16x16x32_bf16 v[16:19], v[166:169], v[200:203], v[16:19]
	v_mfma_f32_16x16x32_bf16 v[4:7], v[148:151], v[210:213], v[4:7]
	v_mfma_f32_16x16x32_bf16 v[0:3], v[166:169], v[210:213], v[0:3]
	s_setprio 0
	s_barrier
	s_add_u32 s26, s26, 0x8000
	s_addc_u32 s27, s27, 0
	s_add_u32 s6, s6, 0x8000
	s_addc_u32 s7, s7, 0
	s_cmp_ge_i32 s40, s10
	s_mov_b32 s28, s40
	s_cbranch_scc1 .LBB0_146

; #define PG8_STAGE(bufoff, gbase, voff) do { _Pragma("unroll") for (int _i = 0; _i < 2; ++_i) \
;         __builtin_amdgcn_global_load_lds((const unsigned*)((const char*)(gbase) + (voff)[_i]), (PG8_LAS unsigned*)(lds + (bufoff) + ldsw + _i * 8192), 16, 0, 0); } while (0)
; #define PG8_LDA(dst, b, h) do { _Pragma("unroll") for (int m = 0; m < 4; ++m) _Pragma("unroll") for (int k = 0; k < 2; ++k) dst[m][k] = *(const PG8_LAS bf16x8*)(lds + PG8_SA(b, h) + aoff + m * 2048 + k * 1024); } while (0)
; #define PG8_LDB(dst, b, h) do { _Pragma("unroll") for (int n = 0; n < 2; ++n) _Pragma("unroll") for (int k = 0; k < 2; ++k) dst[n][k] = *(const PG8_LAS bf16x8*)(lds + PG8_SB(b, h) + boff + n * 2048 + k * 1024); } while (0)
; #define PG8_MMA(ai, bj, At, Bt) do { __builtin_amdgcn_s_setprio(1); _Pragma("unroll") for (int m = 0; m < 4; ++m) _Pragma("unroll") for (int n = 0; n < 2; ++n) _Pragma("unroll") for (int k = 0; k < 2; ++k) \
;         acc[ai][bj][m][n] = __builtin_amdgcn_mfma_f32_16x16x32_bf16(Bt[n][k], At[m][k], acc[ai][bj][m][n], 0, 0, 0); __builtin_amdgcn_s_setprio(0); } while (0)
; #define PG8_WAIT_V(n) asm volatile("s_waitcnt vmcnt(" #n ")" ::: "memory")
; #define PG8_WAIT_L(n) asm volatile("s_waitcnt lgkmcnt(" #n ")" ::: "memory")
; #define PG8_BAR __builtin_amdgcn_s_barrier()
; #define PG8_SCHED __builtin_amdgcn_sched_barrier(0)
; template <class Epi, class Sched, bool ALIGN_EPI = false, bool SP2 = false>
; __device__ __forceinline__ void gemm_phase(PG8_LAS unsigned char* lds, const Gemm g, const Sched& S, const Epi& E, const int tid_in) {
;     ...
;             PG8_LDB(B0, 0, 0); PG8_LDB(B1, 0, 1); PG8_SCHED; PG8_LDA(At, 0, 0); PG8_STAGE(PG8_SA(1, 1), a1 + hstepA, voffA);
;             PG8_WAIT_V(8); PG8_WAIT_L(0); PG8_BAR; PG8_MMA(0, 0, At, B0); PG8_MMA(0, 1, At, B1); PG8_BAR; PG8_SCHED;
;             PG8_LDA(At, 0, 1); PG8_STAGE(PG8_SB(0, 0), b2, voffB); PG8_STAGE(PG8_SB(0, 1), b2 + hstepB, voffB); PG8_STAGE(PG8_SA(0, 0), a2, voffA);
;             PG8_WAIT_V(8); PG8_WAIT_L(0); PG8_BAR; PG8_MMA(1, 0, At, B0); PG8_MMA(1, 1, At, B1); PG8_BAR; PG8_SCHED;
;     ...
;         for (int a = 0; a < 2; ++a)
; #pragma unroll
;             for (int b = 0; b < 2; ++b)
; #pragma unroll
;                 for (int m = 0; m < 4; ++m)
; #pragma unroll
;                     for (int n = 0; n < 2; ++n) acc[a][b][m][n] = (f32x4){0.f, 0.f, 0.f, 0.f};
.LBB0_232:
	s_andn2_b64 vcc, exec, s[26:27]
	s_cbranch_vccnz .Lzero_acc_3
	s_add_u32 s78, s46, s18
	s_addc_u32 s96, s47, s19
	s_add_u32 s97, s48, 0x8000
	s_addc_u32 s6, s49, 0
	s_mov_b64 s[42:43], 0
	s_add_u32 s4, s42, 1
	s_addc_u32 s5, s43, 0
	s_add_u32 s44, s42, 2
	s_addc_u32 s45, s43, 0
	s_lshl_b64 s[48:49], s[44:45], s70
	s_add_u32 s7, s46, s48
	s_addc_u32 s43, s47, s49
	s_cmp_eq_u32 s52, s42
	s_cselect_b32 vcc_lo, s62, s7
	s_cselect_b32 vcc_hi, s63, s43
	s_cselect_b32 s48, s36, s97
	s_cselect_b32 s49, s37, s6
	s_add_u32 s42, vcc_lo, s91
	s_addc_u32 s43, vcc_hi, 0
	s_add_i32 s7, 0, 0x10000
	s_add_i32 s74, 0, 0x14000
	v_add_u32_e32 v108, s7, v244
	v_add_u32_e32 v156, s74, v244
	ds_read_b128 v[64:67], v108
	ds_read_b128 v[76:79], v108 offset:1024
	ds_read_b128 v[88:91], v108 offset:2048
	ds_read_b128 v[108:111], v108 offset:3072
	ds_read_b128 v[144:147], v156
	ds_read_b128 v[148:151], v156 offset:1024
	ds_read_b128 v[152:155], v156 offset:2048
	ds_read_b128 v[156:159], v156 offset:3072
	s_lshl_b64 s[4:5], s[4:5], s70
	s_add_u32 s4, s78, s4
	s_addc_u32 s5, s96, s5
	v_lshl_add_u64 v[192:193], s[4:5], 0, v[210:211]
	s_add_i32 m0, s13, 0xc000
	ds_read_b128 v[160:163], v248
	ds_read_b128 v[164:167], v248 offset:1024
	ds_read_b128 v[168:171], v248 offset:2048
	ds_read_b128 v[172:175], v248 offset:3072
	ds_read_b128 v[176:179], v248 offset:4096
	ds_read_b128 v[180:183], v248 offset:5120
	ds_read_b128 v[184:187], v248 offset:6144
	ds_read_b128 v[188:191], v248 offset:7168
	global_load_lds_dwordx4 v[192:193], off
	v_lshl_add_u64 v[192:193], s[4:5], 0, v[214:215]
	s_add_i32 m0, s13, 0xe000
	s_nop 0
	global_load_lds_dwordx4 v[192:193], off
	s_waitcnt vmcnt(8)
	s_waitcnt lgkmcnt(0)
	s_barrier
	s_setprio 1
	s_waitcnt lgkmcnt(0)
	v_mfma_f32_16x16x32_bf16 v[140:143], v[64:67], v[160:163], 0
	v_mfma_f32_16x16x32_bf16 v[136:139], v[88:91], v[160:163], 0
	v_mfma_f32_16x16x32_bf16 v[124:127], v[64:67], v[168:171], 0
	v_mfma_f32_16x16x32_bf16 v[120:123], v[88:91], v[168:171], 0
	v_mfma_f32_16x16x32_bf16 v[104:107], v[64:67], v[176:179], 0
	v_mfma_f32_16x16x32_bf16 v[100:103], v[88:91], v[176:179], 0
	v_mfma_f32_16x16x32_bf16 v[84:87], v[64:67], v[184:187], 0
	v_mfma_f32_16x16x32_bf16 v[80:83], v[88:91], v[184:187], 0
	v_mfma_f32_16x16x32_bf16 v[140:143], v[76:79], v[164:167], v[140:143]
	v_mfma_f32_16x16x32_bf16 v[136:139], v[108:111], v[164:167], v[136:139]
	v_mfma_f32_16x16x32_bf16 v[124:127], v[76:79], v[172:175], v[124:127]
	v_mfma_f32_16x16x32_bf16 v[120:123], v[108:111], v[172:175], v[120:123]
	v_mfma_f32_16x16x32_bf16 v[104:107], v[76:79], v[180:183], v[104:107]
	v_mfma_f32_16x16x32_bf16 v[100:103], v[108:111], v[180:183], v[100:103]
	v_mfma_f32_16x16x32_bf16 v[84:87], v[76:79], v[188:191], v[84:87]
	v_mfma_f32_16x16x32_bf16 v[80:83], v[108:111], v[188:191], v[80:83]
	s_setprio 0
	s_setprio 1
	v_mfma_f32_16x16x32_bf16 v[132:135], v[144:147], v[160:163], 0
	v_mfma_f32_16x16x32_bf16 v[128:131], v[152:155], v[160:163], 0
	v_mfma_f32_16x16x32_bf16 v[116:119], v[144:147], v[168:171], 0
	v_mfma_f32_16x16x32_bf16 v[112:115], v[152:155], v[168:171], 0
	v_mfma_f32_16x16x32_bf16 v[96:99], v[144:147], v[176:179], 0
	v_mfma_f32_16x16x32_bf16 v[92:95], v[152:155], v[176:179], 0
	v_mfma_f32_16x16x32_bf16 v[72:75], v[144:147], v[184:187], 0
	v_mfma_f32_16x16x32_bf16 v[68:71], v[152:155], v[184:187], 0
	v_mfma_f32_16x16x32_bf16 v[132:135], v[148:151], v[164:167], v[132:135]
	v_mfma_f32_16x16x32_bf16 v[128:131], v[156:159], v[164:167], v[128:131]
	v_mfma_f32_16x16x32_bf16 v[116:119], v[148:151], v[172:175], v[116:119]
	v_mfma_f32_16x16x32_bf16 v[112:115], v[156:159], v[172:175], v[112:115]
	v_mfma_f32_16x16x32_bf16 v[96:99], v[148:151], v[180:183], v[96:99]
	v_mfma_f32_16x16x32_bf16 v[92:95], v[156:159], v[180:183], v[92:95]
	v_mfma_f32_16x16x32_bf16 v[72:75], v[148:151], v[188:191], v[72:75]
	v_mfma_f32_16x16x32_bf16 v[68:71], v[156:159], v[188:191], v[68:71]
	s_setprio 0
	s_barrier
	s_add_i32 s4, s7, s50
	v_lshl_add_u64 v[192:193], s[48:49], 0, v[208:209]
	s_mov_b32 m0, s4
	ds_read_b128 v[160:163], v248 offset:16384
	ds_read_b128 v[164:167], v248 offset:17408
	ds_read_b128 v[168:171], v248 offset:18432
	ds_read_b128 v[172:175], v248 offset:19456
	ds_read_b128 v[176:179], v248 offset:20480
	ds_read_b128 v[180:183], v248 offset:21504
	ds_read_b128 v[184:187], v248 offset:22528
	ds_read_b128 v[188:191], v248 offset:23552
	global_load_lds_dwordx4 v[192:193], off
	s_add_i32 m0, s4, 0x2000
	s_add_u32 s4, s48, s14
	v_lshl_add_u64 v[192:193], s[48:49], 0, v[212:213]
	s_addc_u32 s5, s49, s15
	s_add_i32 s7, s74, s50
	global_load_lds_dwordx4 v[192:193], off
	v_lshl_add_u64 v[192:193], s[4:5], 0, v[208:209]
	s_mov_b32 m0, s7
	s_nop 0
	global_load_lds_dwordx4 v[192:193], off
	v_lshl_add_u64 v[192:193], s[4:5], 0, v[212:213]
	s_add_i32 m0, s7, 0x2000
	s_nop 0
	global_load_lds_dwordx4 v[192:193], off
	v_lshl_add_u64 v[192:193], vcc, 0, v[210:211]
	s_mov_b32 m0, s13
	s_nop 0
	global_load_lds_dwordx4 v[192:193], off
	v_lshl_add_u64 v[192:193], vcc, 0, v[214:215]
	s_mov_b32 m0, s51
	s_nop 0
	global_load_lds_dwordx4 v[192:193], off
	s_waitcnt vmcnt(8)
	s_waitcnt lgkmcnt(0)
	s_barrier
; #define PG8_STAGE(bufoff, gbase, voff) do { _Pragma("unroll") for (int _i = 0; _i < 2; ++_i) \
;         __builtin_amdgcn_global_load_lds((const unsigned*)((const char*)(gbase) + (voff)[_i]), (PG8_LAS unsigned*)(lds + (bufoff) + ldsw + _i * 8192), 16, 0, 0); } while (0)
; #define PG8_LDA(dst, b, h) do { _Pragma("unroll") for (int m = 0; m < 4; ++m) _Pragma("unroll") for (int k = 0; k < 2; ++k) dst[m][k] = *(const PG8_LAS bf16x8*)(lds + PG8_SA(b, h) + aoff + m * 2048 + k * 1024); } while (0)
; #define PG8_LDB(dst, b, h) do { _Pragma("unroll") for (int n = 0; n < 2; ++n) _Pragma("unroll") for (int k = 0; k < 2; ++k) dst[n][k] = *(const PG8_LAS bf16x8*)(lds + PG8_SB(b, h) + boff + n * 2048 + k * 1024); } while (0)
; #define PG8_MMA(ai, bj, At, Bt) do { __builtin_amdgcn_s_setprio(1); _Pragma("unroll") for (int m = 0; m < 4; ++m) _Pragma("unroll") for (int n = 0; n < 2; ++n) _Pragma("unroll") for (int k = 0; k < 2; ++k) \
;         acc[ai][bj][m][n] = __builtin_amdgcn_mfma_f32_16x16x32_bf16(Bt[n][k], At[m][k], acc[ai][bj][m][n], 0, 0, 0); __builtin_amdgcn_s_setprio(0); } while (0)
; #define PG8_WAIT_V(n) asm volatile("s_waitcnt vmcnt(" #n ")" ::: "memory")
; #define PG8_WAIT_L(n) asm volatile("s_waitcnt lgkmcnt(" #n ")" ::: "memory")
; #define PG8_BAR __builtin_amdgcn_s_barrier()
; #define PG8_SCHED __builtin_amdgcn_sched_barrier(0)
; template <class Epi, class Sched, bool ALIGN_EPI = false, bool SP2 = false>
; __device__ __forceinline__ void gemm_phase(PG8_LAS unsigned char* lds, const Gemm g, const Sched& S, const Epi& E, const int tid_in) {
;     ...
;             PG8_WAIT_V(8); PG8_WAIT_L(0); PG8_BAR; PG8_MMA(1, 0, At, B0); PG8_MMA(1, 1, At, B1); PG8_BAR; PG8_SCHED;
;             PG8_LDB(B0, 1, 0); PG8_LDB(B1, 1, 1); PG8_SCHED; PG8_LDA(At, 1, 0); PG8_STAGE(PG8_SA(0, 1), a2 + hstepA, voffA);
;             PG8_WAIT_V(8); PG8_WAIT_L(0); PG8_BAR; PG8_MMA(0, 0, At, B0); PG8_MMA(0, 1, At, B1); PG8_BAR; PG8_SCHED;
	s_setprio 1
	s_waitcnt lgkmcnt(0)
	v_mfma_f32_16x16x32_bf16 v[60:63], v[64:67], v[160:163], 0
	v_mfma_f32_16x16x32_bf16 v[56:59], v[88:91], v[160:163], 0
	v_mfma_f32_16x16x32_bf16 v[44:47], v[64:67], v[168:171], 0
	v_mfma_f32_16x16x32_bf16 v[40:43], v[88:91], v[168:171], 0
	v_mfma_f32_16x16x32_bf16 v[28:31], v[64:67], v[176:179], 0
	v_mfma_f32_16x16x32_bf16 v[24:27], v[88:91], v[176:179], 0
	v_mfma_f32_16x16x32_bf16 v[12:15], v[64:67], v[184:187], 0
	v_mfma_f32_16x16x32_bf16 v[8:11], v[88:91], v[184:187], 0
	v_mfma_f32_16x16x32_bf16 v[60:63], v[76:79], v[164:167], v[60:63]
	v_mfma_f32_16x16x32_bf16 v[56:59], v[108:111], v[164:167], v[56:59]
	v_mfma_f32_16x16x32_bf16 v[44:47], v[76:79], v[172:175], v[44:47]
	v_mfma_f32_16x16x32_bf16 v[40:43], v[108:111], v[172:175], v[40:43]
	v_mfma_f32_16x16x32_bf16 v[28:31], v[76:79], v[180:183], v[28:31]
	v_mfma_f32_16x16x32_bf16 v[24:27], v[108:111], v[180:183], v[24:27]
	v_mfma_f32_16x16x32_bf16 v[12:15], v[76:79], v[188:191], v[12:15]
	v_mfma_f32_16x16x32_bf16 v[8:11], v[108:111], v[188:191], v[8:11]
	s_setprio 0
	s_setprio 1
	v_mfma_f32_16x16x32_bf16 v[52:55], v[144:147], v[160:163], 0
	v_mfma_f32_16x16x32_bf16 v[48:51], v[152:155], v[160:163], 0
	v_mfma_f32_16x16x32_bf16 v[36:39], v[144:147], v[168:171], 0
	v_mfma_f32_16x16x32_bf16 v[32:35], v[152:155], v[168:171], 0
	v_mfma_f32_16x16x32_bf16 v[20:23], v[144:147], v[176:179], 0
	v_mfma_f32_16x16x32_bf16 v[16:19], v[152:155], v[176:179], 0
	v_mfma_f32_16x16x32_bf16 v[4:7], v[144:147], v[184:187], 0
	v_mfma_f32_16x16x32_bf16 v[0:3], v[152:155], v[184:187], 0
	v_mfma_f32_16x16x32_bf16 v[52:55], v[148:151], v[164:167], v[52:55]
	v_mfma_f32_16x16x32_bf16 v[48:51], v[156:159], v[164:167], v[48:51]
	v_mfma_f32_16x16x32_bf16 v[36:39], v[148:151], v[172:175], v[36:39]
	v_mfma_f32_16x16x32_bf16 v[32:35], v[156:159], v[172:175], v[32:35]
	v_mfma_f32_16x16x32_bf16 v[20:23], v[148:151], v[180:183], v[20:23]
	v_mfma_f32_16x16x32_bf16 v[16:19], v[156:159], v[180:183], v[16:19]
	v_mfma_f32_16x16x32_bf16 v[4:7], v[148:151], v[188:191], v[4:7]
	v_mfma_f32_16x16x32_bf16 v[0:3], v[156:159], v[188:191], v[0:3]
	s_setprio 0
	s_barrier
	s_add_i32 s7, 0, 0x18000
	s_add_i32 s74, 0, 0x1c000
	v_add_u32_e32 v108, s7, v244
	v_add_u32_e32 v156, s74, v244
	ds_read_b128 v[64:67], v108
	ds_read_b128 v[76:79], v108 offset:1024
	ds_read_b128 v[88:91], v108 offset:2048
	ds_read_b128 v[108:111], v108 offset:3072
	ds_read_b128 v[144:147], v156
	ds_read_b128 v[148:151], v156 offset:1024
	ds_read_b128 v[152:155], v156 offset:2048
	ds_read_b128 v[156:159], v156 offset:3072
	s_add_u32 s4, vcc_lo, s18
	s_addc_u32 s5, vcc_hi, s19
	s_mov_b32 m0, s64
	v_lshl_add_u64 v[192:193], s[4:5], 0, v[210:211]
	ds_read_b128 v[160:163], v248 offset:32768
	ds_read_b128 v[164:167], v248 offset:33792
	ds_read_b128 v[168:171], v248 offset:34816
	ds_read_b128 v[172:175], v248 offset:35840
	ds_read_b128 v[176:179], v248 offset:36864
	ds_read_b128 v[180:183], v248 offset:37888
	ds_read_b128 v[184:187], v248 offset:38912
	ds_read_b128 v[188:191], v248 offset:39936
	global_load_lds_dwordx4 v[192:193], off
	v_lshl_add_u64 v[192:193], s[4:5], 0, v[214:215]
	s_mov_b32 m0, s86
	s_nop 0
	global_load_lds_dwordx4 v[192:193], off
	s_waitcnt vmcnt(8)
	s_waitcnt lgkmcnt(0)
	s_barrier
	s_setprio 1
	s_waitcnt lgkmcnt(0)
	v_mfma_f32_16x16x32_bf16 v[140:143], v[64:67], v[160:163], v[140:143]
	v_mfma_f32_16x16x32_bf16 v[136:139], v[88:91], v[160:163], v[136:139]
	v_mfma_f32_16x16x32_bf16 v[124:127], v[64:67], v[168:171], v[124:127]
	v_mfma_f32_16x16x32_bf16 v[120:123], v[88:91], v[168:171], v[120:123]
	v_mfma_f32_16x16x32_bf16 v[104:107], v[64:67], v[176:179], v[104:107]
	v_mfma_f32_16x16x32_bf16 v[100:103], v[88:91], v[176:179], v[100:103]
	v_mfma_f32_16x16x32_bf16 v[84:87], v[64:67], v[184:187], v[84:87]
	v_mfma_f32_16x16x32_bf16 v[80:83], v[88:91], v[184:187], v[80:83]
	v_mfma_f32_16x16x32_bf16 v[140:143], v[76:79], v[164:167], v[140:143]
	v_mfma_f32_16x16x32_bf16 v[136:139], v[108:111], v[164:167], v[136:139]
	v_mfma_f32_16x16x32_bf16 v[124:127], v[76:79], v[172:175], v[124:127]
	v_mfma_f32_16x16x32_bf16 v[120:123], v[108:111], v[172:175], v[120:123]
	v_mfma_f32_16x16x32_bf16 v[104:107], v[76:79], v[180:183], v[104:107]
	v_mfma_f32_16x16x32_bf16 v[100:103], v[108:111], v[180:183], v[100:103]
	v_mfma_f32_16x16x32_bf16 v[84:87], v[76:79], v[188:191], v[84:87]
	v_mfma_f32_16x16x32_bf16 v[80:83], v[108:111], v[188:191], v[80:83]
	s_setprio 0
	s_setprio 1
	v_mfma_f32_16x16x32_bf16 v[132:135], v[144:147], v[160:163], v[132:135]
	v_mfma_f32_16x16x32_bf16 v[128:131], v[152:155], v[160:163], v[128:131]
	v_mfma_f32_16x16x32_bf16 v[116:119], v[144:147], v[168:171], v[116:119]
	v_mfma_f32_16x16x32_bf16 v[112:115], v[152:155], v[168:171], v[112:115]
	v_mfma_f32_16x16x32_bf16 v[96:99], v[144:147], v[176:179], v[96:99]
	v_mfma_f32_16x16x32_bf16 v[92:95], v[152:155], v[176:179], v[92:95]
	v_mfma_f32_16x16x32_bf16 v[72:75], v[144:147], v[184:187], v[72:75]
	v_mfma_f32_16x16x32_bf16 v[68:71], v[152:155], v[184:187], v[68:71]
	v_mfma_f32_16x16x32_bf16 v[132:135], v[148:151], v[164:167], v[132:135]
	v_mfma_f32_16x16x32_bf16 v[128:131], v[156:159], v[164:167], v[128:131]
	v_mfma_f32_16x16x32_bf16 v[116:119], v[148:151], v[172:175], v[116:119]
	v_mfma_f32_16x16x32_bf16 v[112:115], v[156:159], v[172:175], v[112:115]
	v_mfma_f32_16x16x32_bf16 v[96:99], v[148:151], v[180:183], v[96:99]
	v_mfma_f32_16x16x32_bf16 v[92:95], v[156:159], v[180:183], v[92:95]
	v_mfma_f32_16x16x32_bf16 v[72:75], v[148:151], v[188:191], v[72:75]
	v_mfma_f32_16x16x32_bf16 v[68:71], v[156:159], v[188:191], v[68:71]
	s_setprio 0
	s_barrier
; #define PG8_STAGE(bufoff, gbase, voff) do { _Pragma("unroll") for (int _i = 0; _i < 2; ++_i) \
;         __builtin_amdgcn_global_load_lds((const unsigned*)((const char*)(gbase) + (voff)[_i]), (PG8_LAS unsigned*)(lds + (bufoff) + ldsw + _i * 8192), 16, 0, 0); } while (0)
; #define PG8_LDA(dst, b, h) do { _Pragma("unroll") for (int m = 0; m < 4; ++m) _Pragma("unroll") for (int k = 0; k < 2; ++k) dst[m][k] = *(const PG8_LAS bf16x8*)(lds + PG8_SA(b, h) + aoff + m * 2048 + k * 1024); } while (0)
; #define PG8_MMA(ai, bj, At, Bt) do { __builtin_amdgcn_s_setprio(1); _Pragma("unroll") for (int m = 0; m < 4; ++m) _Pragma("unroll") for (int n = 0; n < 2; ++n) _Pragma("unroll") for (int k = 0; k < 2; ++k) \
;         acc[ai][bj][m][n] = __builtin_amdgcn_mfma_f32_16x16x32_bf16(Bt[n][k], At[m][k], acc[ai][bj][m][n], 0, 0, 0); __builtin_amdgcn_s_setprio(0); } while (0)
; #define PG8_WAIT_V(n) asm volatile("s_waitcnt vmcnt(" #n ")" ::: "memory")
; #define PG8_WAIT_L(n) asm volatile("s_waitcnt lgkmcnt(" #n ")" ::: "memory")
; #define PG8_BAR __builtin_amdgcn_s_barrier()
; #define PG8_SCHED __builtin_amdgcn_sched_barrier(0)
; template <class Epi, class Sched, bool ALIGN_EPI = false, bool SP2 = false>
; __device__ __forceinline__ void gemm_phase(PG8_LAS unsigned char* lds, const Gemm g, const Sched& S, const Epi& E, const int tid_in) {
;     ...
;         for (int t = 0; t < nt; t += 2) {
;             const bool last = (t == nt - 2);
;             const char* a1 = cA + (size_t)(t + 1) * kstepA;
;             const char* a2 = last ? nA : cA + (size_t)(t + 2) * kstepA; const char* b2 = last ? nB : cB + (size_t)(t + 2) * kstepB;
;             const char* a3 = a2 + kstepA; const char* b3 = b2 + kstepB;
;     ...
;             PG8_LDA(At, 1, 1); PG8_STAGE(PG8_SB(1, 0), b3, voffB); PG8_STAGE(PG8_SB(1, 1), b3 + hstepB, voffB); PG8_STAGE(PG8_SA(1, 0), a3, voffA);
;             PG8_WAIT_V(8); PG8_WAIT_L(0); PG8_BAR; PG8_MMA(1, 0, At, B0); PG8_MMA(1, 1, At, B1); PG8_BAR; PG8_SCHED;
	s_add_u32 s4, s48, 0x4000
	s_addc_u32 s5, s49, 0
	s_add_i32 s7, s7, s50
	v_lshl_add_u64 v[192:193], s[4:5], 0, v[208:209]
	s_mov_b32 m0, s7
	ds_read_b128 v[160:163], v248 offset:49152
	ds_read_b128 v[164:167], v248 offset:50176
	ds_read_b128 v[168:171], v248 offset:51200
	ds_read_b128 v[172:175], v248 offset:52224
	ds_read_b128 v[176:179], v248 offset:53248
	ds_read_b128 v[180:183], v248 offset:54272
	ds_read_b128 v[184:187], v248 offset:55296
	ds_read_b128 v[188:191], v248 offset:56320
	global_load_lds_dwordx4 v[192:193], off
	s_add_i32 m0, s7, 0x2000
	v_lshl_add_u64 v[192:193], s[4:5], 0, v[212:213]
	s_add_u32 s4, s4, s14
	s_addc_u32 s5, s5, s15
	s_add_i32 s7, s74, s50
	global_load_lds_dwordx4 v[192:193], off
	v_lshl_add_u64 v[192:193], s[4:5], 0, v[208:209]
	s_mov_b32 m0, s7
	s_nop 0
	global_load_lds_dwordx4 v[192:193], off
	v_lshl_add_u64 v[192:193], s[4:5], 0, v[212:213]
	s_add_i32 m0, s7, 0x2000
	s_nop 0
	global_load_lds_dwordx4 v[192:193], off
	v_lshl_add_u64 v[192:193], s[42:43], 0, v[210:211]
	s_mov_b32 m0, s68
	s_nop 0
	global_load_lds_dwordx4 v[192:193], off
	v_lshl_add_u64 v[192:193], s[42:43], 0, v[214:215]
	s_mov_b32 m0, s69
	s_nop 0
	global_load_lds_dwordx4 v[192:193], off
	s_waitcnt vmcnt(8)
	s_waitcnt lgkmcnt(0)
	s_barrier
	s_setprio 1
	s_waitcnt lgkmcnt(0)
	v_mfma_f32_16x16x32_bf16 v[60:63], v[64:67], v[160:163], v[60:63]
	v_mfma_f32_16x16x32_bf16 v[56:59], v[88:91], v[160:163], v[56:59]
	v_mfma_f32_16x16x32_bf16 v[44:47], v[64:67], v[168:171], v[44:47]
	v_mfma_f32_16x16x32_bf16 v[40:43], v[88:91], v[168:171], v[40:43]
	v_mfma_f32_16x16x32_bf16 v[28:31], v[64:67], v[176:179], v[28:31]
	v_mfma_f32_16x16x32_bf16 v[24:27], v[88:91], v[176:179], v[24:27]
	v_mfma_f32_16x16x32_bf16 v[12:15], v[64:67], v[184:187], v[12:15]
	v_mfma_f32_16x16x32_bf16 v[8:11], v[88:91], v[184:187], v[8:11]
	v_mfma_f32_16x16x32_bf16 v[60:63], v[76:79], v[164:167], v[60:63]
	v_mfma_f32_16x16x32_bf16 v[56:59], v[108:111], v[164:167], v[56:59]
	v_mfma_f32_16x16x32_bf16 v[44:47], v[76:79], v[172:175], v[44:47]
	v_mfma_f32_16x16x32_bf16 v[40:43], v[108:111], v[172:175], v[40:43]
	v_mfma_f32_16x16x32_bf16 v[28:31], v[76:79], v[180:183], v[28:31]
	v_mfma_f32_16x16x32_bf16 v[24:27], v[108:111], v[180:183], v[24:27]
	v_mfma_f32_16x16x32_bf16 v[12:15], v[76:79], v[188:191], v[12:15]
	v_mfma_f32_16x16x32_bf16 v[8:11], v[108:111], v[188:191], v[8:11]
	s_setprio 0
	s_setprio 1
	v_mfma_f32_16x16x32_bf16 v[52:55], v[144:147], v[160:163], v[52:55]
	v_mfma_f32_16x16x32_bf16 v[48:51], v[152:155], v[160:163], v[48:51]
	v_mfma_f32_16x16x32_bf16 v[36:39], v[144:147], v[168:171], v[36:39]
	v_mfma_f32_16x16x32_bf16 v[32:35], v[152:155], v[168:171], v[32:35]
	v_mfma_f32_16x16x32_bf16 v[20:23], v[144:147], v[176:179], v[20:23]
	v_mfma_f32_16x16x32_bf16 v[16:19], v[152:155], v[176:179], v[16:19]
	v_mfma_f32_16x16x32_bf16 v[4:7], v[144:147], v[184:187], v[4:7]
	v_mfma_f32_16x16x32_bf16 v[0:3], v[152:155], v[184:187], v[0:3]
	v_mfma_f32_16x16x32_bf16 v[52:55], v[148:151], v[164:167], v[52:55]
	v_mfma_f32_16x16x32_bf16 v[48:51], v[156:159], v[164:167], v[48:51]
	v_mfma_f32_16x16x32_bf16 v[36:39], v[148:151], v[172:175], v[36:39]
	v_mfma_f32_16x16x32_bf16 v[32:35], v[156:159], v[172:175], v[32:35]
	v_mfma_f32_16x16x32_bf16 v[20:23], v[148:151], v[180:183], v[20:23]
	v_mfma_f32_16x16x32_bf16 v[16:19], v[156:159], v[180:183], v[16:19]
	v_mfma_f32_16x16x32_bf16 v[4:7], v[148:151], v[188:191], v[4:7]
	v_mfma_f32_16x16x32_bf16 v[0:3], v[156:159], v[188:191], v[0:3]
	s_setprio 0
	s_barrier
	s_add_u32 s97, s97, 0x8000
	s_addc_u32 s6, s6, 0
	s_cmp_ge_i32 s44, s12
	s_mov_b64 s[42:43], s[44:45]
	s_cbranch_scc1 .LBB0_235
